# weight transposes split: phase 0 does only in-proj tiles (it<128), rest done by blocks 32..255 in phase-2 tail
# baseline (speedup 1.0000x reference)
.LBB0_1052:
	s_barrier
	v_readlane_b32 s32, v249, 18
	s_cmpk_eq_i32 s32, 0x100
	s_cbranch_scc0 .Ltr2_done
	s_cmpk_lt_i32 s92, 0x20
	s_cbranch_scc1 .Ltr2_done
	v_mov_b32_e32 v46, v163
	s_waitcnt vmcnt(0) lgkmcnt(0)
	v_ashrrev_i32_e32 v1, 7, v46
	s_movk_i32 s0, 0x4100
	v_mul_lo_u32 v0, v1, s0
	v_add_u32_e32 v3, 0, v0
	v_and_b32_e32 v2, 15, v46
	v_lshlrev_b32_e32 v0, 2, v2
	v_lshl_add_u32 v4, v2, 4, v3
	v_bfe_u32 v11, v46, 1, 6
	v_and_b32_e32 v2, 0x60, v46
	v_and_or_b32 v12, v11, 15, v2
	v_lshlrev_b32_e32 v2, 5, v46
	v_bfe_u32 v10, v46, 4, 3
	v_and_b32_e32 v2, 32, v2
	v_lshl_add_u32 v3, v11, 2, v3
	v_mul_u32_u24_e32 v5, 0x104, v2
	v_mul_u32_u24_e32 v6, 0x104, v10
	v_readlane_b32 s0, v254, 20
	v_lshlrev_b32_e32 v160, 2, v0
	v_add_u32_e32 v14, v4, v6
	v_add_u32_e32 v13, s0, v1
	v_add_u32_e32 v13, 0x180, v13
	v_lshlrev_b32_e32 v0, 1, v2
	v_add_u32_e32 v15, v3, v5
	s_add_i32 s10, s92, 0x60
	s_branch .Ltr2_1076
.Ltr2_1075:
	s_or_b64 exec, exec, s[0:1]
	v_readlane_b32 s0, v249, 12
	v_readlane_b32 s1, v249, 13
	v_ashrrev_i32_e32 v1, 31, v6
	v_readlane_b32 s2, v249, 14
	v_readlane_b32 s3, v249, 15
	v_mul_lo_u32 v7, v5, v6
	v_mul_lo_u32 v1, v4, v1
	v_mad_u64_u32 v[4:5], s[0:1], v4, v6, 0
	v_lshl_add_u64 v[2:3], s[2:3], 0, v[2:3]
	v_add3_u32 v5, v5, v1, v7
	v_lshl_add_u64 v[2:3], v[4:5], 1, v[2:3]
	v_add_u32_e32 v16, 0x400, v15
	v_lshl_add_u64 v[2:3], v[8:9], 1, v[2:3]
	ds_read2_b32 v[4:5], v15 offset1:65
	ds_read2_b32 v[6:7], v15 offset0:130 offset1:195
	ds_read2_b32 v[8:9], v16 offset0:4 offset1:69
	ds_read2_b32 v[16:17], v16 offset0:134 offset1:199
	v_mov_b32_e32 v1, v161
	v_lshl_add_u64 v[18:19], v[2:3], 0, v[0:1]
	v_add_u32_e32 v1, 0x800, v15
	s_waitcnt lgkmcnt(3)
	v_cvt_pk_bf16_f32 v2, v4, v5
	s_waitcnt lgkmcnt(2)
	v_cvt_pk_bf16_f32 v3, v6, v7
	s_waitcnt lgkmcnt(1)
	v_cvt_pk_bf16_f32 v4, v8, v9
	s_waitcnt lgkmcnt(0)
	v_cvt_pk_bf16_f32 v5, v16, v17
	ds_read2_b32 v[6:7], v1 offset0:8 offset1:73
	ds_read2_b32 v[8:9], v1 offset0:138 offset1:203
	v_add_u32_e32 v1, 0xc00, v15
	ds_read2_b32 v[16:17], v1 offset0:12 offset1:77
	ds_read2_b32 v[20:21], v1 offset0:142 offset1:207
	v_add_u32_e32 v1, 0x1000, v15
	global_store_dwordx4 v[18:19], v[2:5], off
	s_movk_i32 s6, 0xe0
	s_add_i32 s10, s10, s6
	s_waitcnt lgkmcnt(3)
	v_cvt_pk_bf16_f32 v2, v6, v7
	s_waitcnt lgkmcnt(2)
	v_cvt_pk_bf16_f32 v3, v8, v9
	s_waitcnt lgkmcnt(1)
	v_cvt_pk_bf16_f32 v4, v16, v17
	s_waitcnt lgkmcnt(0)
	v_cvt_pk_bf16_f32 v5, v20, v21
	ds_read2_b32 v[6:7], v1 offset0:16 offset1:81
	ds_read2_b32 v[8:9], v1 offset0:146 offset1:211
	v_add_u32_e32 v1, 0x1400, v15
	ds_read2_b32 v[16:17], v1 offset0:20 offset1:85
	ds_read2_b32 v[20:21], v1 offset0:150 offset1:215
	v_add_u32_e32 v1, 0x1800, v15
	global_store_dwordx4 v[18:19], v[2:5], off offset:16
	s_movk_i32 s0, 0x380
	s_cmpk_gt_i32 s10, 0x5ff
	s_waitcnt lgkmcnt(3)
	v_cvt_pk_bf16_f32 v2, v6, v7
	s_waitcnt lgkmcnt(2)
	v_cvt_pk_bf16_f32 v3, v8, v9
	s_waitcnt lgkmcnt(1)
	v_cvt_pk_bf16_f32 v4, v16, v17
	s_waitcnt lgkmcnt(0)
	v_cvt_pk_bf16_f32 v5, v20, v21
	ds_read2_b32 v[6:7], v1 offset0:24 offset1:89
	ds_read2_b32 v[8:9], v1 offset0:154 offset1:219
	v_add_u32_e32 v1, 0x1c00, v15
	ds_read2_b32 v[16:17], v1 offset0:28 offset1:93
	ds_read2_b32 v[20:21], v1 offset0:158 offset1:223
	v_add_u32_e32 v13, s0, v13
	v_readlane_b32 s4, v249, 16
	v_readlane_b32 s5, v249, 17
	v_readlane_b32 s7, v249, 19
	global_store_dwordx4 v[18:19], v[2:5], off offset:32
	s_waitcnt lgkmcnt(3)
	s_nop 0
	v_cvt_pk_bf16_f32 v2, v6, v7
	s_waitcnt lgkmcnt(2)
	v_cvt_pk_bf16_f32 v3, v8, v9
	s_waitcnt lgkmcnt(1)
	v_cvt_pk_bf16_f32 v4, v16, v17
	s_waitcnt lgkmcnt(0)
	v_cvt_pk_bf16_f32 v5, v20, v21
	global_store_dwordx4 v[18:19], v[2:5], off offset:48
	s_barrier
	s_cbranch_scc1 .Ltr2_done

.Ltr2_done:
.LBB0_1053:
	v_readlane_b32 s36, v251, 28
	s_mov_b64 s[0:1], 0
	v_readlane_b32 s37, v251, 29

.LBB0_1073:
	v_readlane_b32 s0, v250, 46
	v_mov_b32_e32 v46, v163
	v_readlane_b32 s1, v250, 47
	s_andn2_b64 vcc, exec, s[0:1]
	s_cbranch_vccnz .LBB0_1108
	v_readlane_b32 s32, v249, 18
	s_cmpk_eq_i32 s32, 0x100
	s_cbranch_scc0 .Ltr0_full
	s_cmpk_gt_i32 s92, 0x7f
	s_cbranch_scc1 .LBB0_1108
	s_movk_i32 s32, 0x7f
	s_branch .Ltr0_go
.Ltr0_full:
	s_movk_i32 s32, 0x5ff
.Ltr0_go:
	s_waitcnt vmcnt(0) lgkmcnt(0)
	v_ashrrev_i32_e32 v1, 7, v46
	s_movk_i32 s0, 0x4100
	v_mul_lo_u32 v0, v1, s0
	v_add_u32_e32 v3, 0, v0
	v_and_b32_e32 v2, 15, v46
	v_lshlrev_b32_e32 v0, 2, v2
	v_lshl_add_u32 v4, v2, 4, v3
	v_bfe_u32 v11, v46, 1, 6
	v_and_b32_e32 v2, 0x60, v46
	v_and_or_b32 v12, v11, 15, v2
	v_lshlrev_b32_e32 v2, 5, v46
	v_bfe_u32 v10, v46, 4, 3
	v_and_b32_e32 v2, 32, v2
	v_lshl_add_u32 v3, v11, 2, v3
	v_mul_u32_u24_e32 v5, 0x104, v2
	v_mul_u32_u24_e32 v6, 0x104, v10
	v_readlane_b32 s0, v254, 20
	v_lshlrev_b32_e32 v160, 2, v0
	v_add_u32_e32 v14, v4, v6
	v_add_u32_e32 v13, s0, v1
	v_lshlrev_b32_e32 v0, 1, v2
	v_add_u32_e32 v15, v3, v5
	s_mov_b32 s10, s92
	s_branch .LBB0_1076
.LBB0_1075:
	s_or_b64 exec, exec, s[0:1]
	v_readlane_b32 s0, v249, 12
	v_readlane_b32 s1, v249, 13
	v_ashrrev_i32_e32 v1, 31, v6
	v_readlane_b32 s2, v249, 14
	v_readlane_b32 s3, v249, 15
	v_mul_lo_u32 v7, v5, v6
	v_mul_lo_u32 v1, v4, v1
	v_mad_u64_u32 v[4:5], s[0:1], v4, v6, 0
	v_lshl_add_u64 v[2:3], s[2:3], 0, v[2:3]
	v_add3_u32 v5, v5, v1, v7
	v_lshl_add_u64 v[2:3], v[4:5], 1, v[2:3]
	v_add_u32_e32 v16, 0x400, v15
	v_lshl_add_u64 v[2:3], v[8:9], 1, v[2:3]
	ds_read2_b32 v[4:5], v15 offset1:65
	ds_read2_b32 v[6:7], v15 offset0:130 offset1:195
	ds_read2_b32 v[8:9], v16 offset0:4 offset1:69
	ds_read2_b32 v[16:17], v16 offset0:134 offset1:199
	v_mov_b32_e32 v1, v161
	v_lshl_add_u64 v[18:19], v[2:3], 0, v[0:1]
	v_add_u32_e32 v1, 0x800, v15
	s_waitcnt lgkmcnt(3)
	v_cvt_pk_bf16_f32 v2, v4, v5
	s_waitcnt lgkmcnt(2)
	v_cvt_pk_bf16_f32 v3, v6, v7
	s_waitcnt lgkmcnt(1)
	v_cvt_pk_bf16_f32 v4, v8, v9
	s_waitcnt lgkmcnt(0)
	v_cvt_pk_bf16_f32 v5, v16, v17
	ds_read2_b32 v[6:7], v1 offset0:8 offset1:73
	ds_read2_b32 v[8:9], v1 offset0:138 offset1:203
	v_add_u32_e32 v1, 0xc00, v15
	ds_read2_b32 v[16:17], v1 offset0:12 offset1:77
	ds_read2_b32 v[20:21], v1 offset0:142 offset1:207
	v_add_u32_e32 v1, 0x1000, v15
	global_store_dwordx4 v[18:19], v[2:5], off
	v_readlane_b32 s6, v249, 18
	s_add_i32 s10, s10, s6
	s_waitcnt lgkmcnt(3)
	v_cvt_pk_bf16_f32 v2, v6, v7
	s_waitcnt lgkmcnt(2)
	v_cvt_pk_bf16_f32 v3, v8, v9
	s_waitcnt lgkmcnt(1)
	v_cvt_pk_bf16_f32 v4, v16, v17
	s_waitcnt lgkmcnt(0)
	v_cvt_pk_bf16_f32 v5, v20, v21
	ds_read2_b32 v[6:7], v1 offset0:16 offset1:81
	ds_read2_b32 v[8:9], v1 offset0:146 offset1:211
	v_add_u32_e32 v1, 0x1400, v15
	ds_read2_b32 v[16:17], v1 offset0:20 offset1:85
	ds_read2_b32 v[20:21], v1 offset0:150 offset1:215
	v_add_u32_e32 v1, 0x1800, v15
	global_store_dwordx4 v[18:19], v[2:5], off offset:16
	v_readlane_b32 s0, v254, 21
	s_cmp_gt_i32 s10, s32
	s_waitcnt lgkmcnt(3)
	v_cvt_pk_bf16_f32 v2, v6, v7
	s_waitcnt lgkmcnt(2)
	v_cvt_pk_bf16_f32 v3, v8, v9
	s_waitcnt lgkmcnt(1)
	v_cvt_pk_bf16_f32 v4, v16, v17
	s_waitcnt lgkmcnt(0)
	v_cvt_pk_bf16_f32 v5, v20, v21
	ds_read2_b32 v[6:7], v1 offset0:24 offset1:89
	ds_read2_b32 v[8:9], v1 offset0:154 offset1:219
	v_add_u32_e32 v1, 0x1c00, v15
	ds_read2_b32 v[16:17], v1 offset0:28 offset1:93
	ds_read2_b32 v[20:21], v1 offset0:158 offset1:223
	v_add_u32_e32 v13, s0, v13
	v_readlane_b32 s4, v249, 16
	v_readlane_b32 s5, v249, 17
	v_readlane_b32 s7, v249, 19
	global_store_dwordx4 v[18:19], v[2:5], off offset:32
	s_waitcnt lgkmcnt(3)
	s_nop 0
	v_cvt_pk_bf16_f32 v2, v6, v7
	s_waitcnt lgkmcnt(2)
	v_cvt_pk_bf16_f32 v3, v8, v9
	s_waitcnt lgkmcnt(1)
	v_cvt_pk_bf16_f32 v4, v16, v17
	s_waitcnt lgkmcnt(0)
	v_cvt_pk_bf16_f32 v5, v20, v21
	global_store_dwordx4 v[18:19], v[2:5], off offset:48
	s_barrier
	s_cbranch_scc1 .LBB0_1108
